# strategy 4 on the SSD phase: static s_setprio 1 for waves 4-7 (the waves with 3-4 diagonal/off-diagonal blocks) so the heavy SIMD partner wins arbitration
# baseline (speedup 1.0000x reference)
.LBB0_306:
	s_cmpk_lt_u32 s93, 0x100
	s_cbranch_scc1 .Lssd_prio_skip
	s_setprio 1

.LBB0_362:
	s_setprio 0
	v_readlane_b32 s94, v253, 54
	v_readlane_b32 s95, v253, 55
	s_mov_b64 s[2:3], s[94:95]
	v_mov_b32_e32 v0, v1
	s_getreg_b32 s4, hwreg(HW_REG_XCC_ID, 0, 4)
	s_waitcnt vmcnt(0)
	v_readlane_b32 s93, v253, 56
	v_mbcnt_lo_u32_b32 v0, -1, v0
	v_mbcnt_hi_u32_b32 v0, -1, v0
	v_sub_u32_e32 v0, 0, v0
	v_cmp_eq_u32_e32 vcc, s93, v0
	s_barrier
	s_mov_b64 s[0:1], exec
	v_readlane_b32 s56, v253, 1
	v_readlane_b32 s57, v253, 2
	v_readlane_b32 s59, v253, 4
	v_readlane_b32 s62, v254, 14
	s_and_b64 s[6:7], s[0:1], vcc
	v_readlane_b32 s92, v253, 53
	v_readlane_b32 s58, v253, 3
	v_readlane_b32 s96, v253, 57
	v_readlane_b32 s74, v254, 6
	v_readlane_b32 s76, v254, 8
	v_readlane_b32 s72, v253, 61
	v_readlane_b32 s73, v253, 62
	s_movk_i32 s82, 0x1600
	v_readlane_b32 s83, v253, 63
	v_readlane_b32 s84, v254, 0
	s_movk_i32 s85, 0x1e1
	s_movk_i32 s56, 0x61
	s_movk_i32 s86, 0x2c1
	v_readlane_b32 s87, v254, 1
	v_readlane_b32 s90, v254, 4
	v_readlane_b32 s57, v254, 5
	s_movk_i32 s25, 0x88
	s_movk_i32 s59, 0x600
	v_readlane_b32 s63, v254, 15
	s_mov_b32 s60, 0x3e16c740
	s_mov_b64 s[66:67], 0x80000
	s_mov_b64 s[68:69], 0x90000
	s_mov_b64 s[70:71], 0xa0000
	s_mov_b64 s[54:55], 0xb0000
	v_mov_b32_e32 v234, 0x1000
	v_mov_b32_e32 v235, 0x2000
	v_mov_b32_e32 v236, 1
	v_mov_b64_e32 v[238:239], 0x400
	v_mov_b64_e32 v[240:241], 0x3ff
	v_readlane_b32 s75, v254, 7
	s_mov_b64 exec, s[6:7]
	s_cbranch_execz .LBB0_414
	v_mov_b32_e32 v0, s90
	s_load_dwordx2 s[2:3], s[2:3], 0xc0
	s_waitcnt vmcnt(0) expcnt(0) lgkmcnt(0)
	ds_read_b32 v3, v0
	v_mov_b32_e32 v0, s57
	ds_read_b32 v2, v0
	s_and_b32 s33, s4, 15
	s_waitcnt lgkmcnt(1)
	v_cmp_ne_u32_e32 vcc, 0, v3
	s_cbranch_vccnz .LBB0_378
	s_add_u32 s4, s2, 0x3a600200
	s_addc_u32 s5, s3, 0
	s_add_u32 s6, s2, 0x3a600400
	s_addc_u32 s7, s3, 0
	s_add_u32 s8, s2, 0x3a600500
	s_addc_u32 s9, s3, 0
	s_add_u32 s10, s2, 0x3a600600
	s_addc_u32 s11, s3, 0
	s_add_u32 s12, s2, 0x3a600700
	s_addc_u32 s13, s3, 0
	s_add_u32 s14, s2, 0x3a600800
	s_addc_u32 s15, s3, 0
	s_add_u32 s16, s2, 0x3a600900
	s_addc_u32 s17, s3, 0
	s_add_u32 s18, s2, 0x3a600a00
	s_addc_u32 s19, s3, 0
	s_add_u32 s20, s2, 0x3a600b00
	s_addc_u32 s21, s3, 0
	s_add_u32 s22, s2, 0x3a600c00
	s_addc_u32 s23, s3, 0
	s_add_u32 s24, s2, 0x3a600d00
	s_addc_u32 s25, s3, 0
	s_add_u32 s26, s2, 0x3a600e00
	s_addc_u32 s27, s3, 0
	s_add_u32 s28, s2, 0x3a600f00
	s_addc_u32 s29, s3, 0
	s_add_u32 s34, s2, 0x3a601000
	s_addc_u32 s35, s3, 0
	s_add_u32 s36, s2, 0x3a601100
	s_addc_u32 s37, s3, 0
	s_add_u32 s38, s2, 0x3a601200
	s_addc_u32 s39, s3, 0
	s_add_u32 s40, s2, 0x3a601300
	s_addc_u32 s41, s3, 0
	s_mov_b32 s48, 1
	s_branch .LBB0_366
